# phase_h token loop rewritten by hand: two consecutive tokens per wave share one fetch of the modulation vectors, all loads of an iteration issued up front
# speedup vs baseline: 1.0939x; 1.0049x over previous
.LBB0_291:
	v_writelane_b32 v255, s0, 47
	v_mov_b32_e32 v0, v235
	s_nop 0
	v_writelane_b32 v255, s1, 48
	s_xor_b64 s[0:1], s[0:1], -1
	v_writelane_b32 v255, s0, 49
	s_nop 1
	v_writelane_b32 v255, s1, 50
	v_readfirstlane_b32 s0, v234
	s_lshr_b32 s0, s0, 8
	s_add_i32 s12, s0, s92
	s_mul_i32 s1, s52, 5
	s_cmpk_gt_i32 s12, 0xbff
	v_writelane_b32 v255, s1, 51
	s_cbranch_scc1 .LBB0_301
	v_ashrrev_i32_e32 v1, 6, v0
	v_lshlrev_b32_e32 v0, 2, v0
	v_cmp_lt_i32_e32 vcc, v246, v239
	s_waitcnt vmcnt(34)
	v_and_b32_e32 v16, 0xfc, v0
	v_readlane_b32 s16, v254, 12
	v_cndmask_b32_e32 v0, v237, v246, vcc
	v_lshlrev_b32_e32 v17, 2, v0
	v_xor_b32_e32 v0, 16, v237
	v_cmp_lt_i32_e32 vcc, v0, v239
	v_lshlrev_b32_e32 v192, 2, v16
	v_readlane_b32 s17, v254, 13
	v_cndmask_b32_e32 v0, v237, v0, vcc
	s_waitcnt vmcnt(3)
	v_lshlrev_b32_e32 v40, 2, v0
	v_xor_b32_e32 v0, 8, v237
	v_cmp_lt_i32_e32 vcc, v0, v239
	v_readlane_b32 s18, v254, 14
	v_readlane_b32 s19, v254, 15
	v_cndmask_b32_e32 v0, v237, v0, vcc
	v_lshlrev_b32_e32 v41, 2, v0
	v_xor_b32_e32 v0, 4, v237
	v_cmp_lt_i32_e32 vcc, v0, v239
	v_readlane_b32 s20, v254, 16
	v_readlane_b32 s21, v254, 17
	v_cndmask_b32_e32 v0, v237, v0, vcc
	v_readlane_b32 s22, v254, 18
	v_readlane_b32 s23, v254, 19
	v_readlane_b32 s24, v254, 20
	v_readlane_b32 s25, v254, 21
	v_readlane_b32 s26, v254, 22
	v_readlane_b32 s27, v254, 23
	v_readlane_b32 s28, v254, 24
	v_readlane_b32 s29, v254, 25
	v_readlane_b32 s30, v254, 26
	v_readlane_b32 s31, v254, 27
	v_lshlrev_b32_e32 v42, 2, v0
	v_xor_b32_e32 v0, 2, v237
	v_lshl_add_u64 v[18:19], s[24:25], 0, v[192:193]
	v_readlane_b32 s2, v253, 58
	v_readlane_b32 s16, v253, 42
	v_cmp_lt_i32_e32 vcc, v0, v239
	s_lshl_b32 s90, s52, 10
	v_readlane_b32 s3, v253, 59
	v_readlane_b32 s30, v253, 56
	v_readlane_b32 s31, v253, 57
	v_cndmask_b32_e32 v0, v237, v0, vcc
	v_lshl_add_u64 v[22:23], s[2:3], 0, v[192:193]
	s_lshl_b64 s[2:3], s[90:91], 2
	s_mov_b64 s[86:87], s[30:31]
	v_lshlrev_b32_e32 v43, 2, v0
	v_xor_b32_e32 v0, 1, v237
	s_add_u32 s2, s86, s2
	v_cmp_lt_i32_e32 vcc, v0, v239
	v_readlane_b32 s44, v253, 0
	s_addc_u32 s3, s87, s3
	s_lshl_b32 s0, s0, 2
	v_readlane_b32 s1, v255, 31
	v_cndmask_b32_e32 v0, v237, v0, vcc
	v_readlane_b32 s50, v253, 6
	v_readlane_b32 s51, v253, 7
	s_add_i32 s0, s0, s1
	s_waitcnt vmcnt(2)
	v_lshlrev_b32_e32 v44, 2, v0
	v_or_b32_e32 v0, 0x100, v16
	v_or_b32_e32 v2, 0x200, v16
	v_or_b32_e32 v4, 0x300, v16
	v_lshl_add_u64 v[20:21], s[50:51], 0, v[192:193]
	v_lshl_add_u64 v[24:25], s[2:3], 0, v[192:193]
	v_lshlrev_b32_e32 v192, 1, v16
	v_add_u32_e32 v28, s0, v1
	v_lshl_add_u64 v[26:27], s[56:57], 0, v[192:193]
	v_lshlrev_b32_e32 v45, 9, v28
	v_lshlrev_b32_e32 v46, 3, v28
	v_lshlrev_b32_e32 v30, 2, v0
	v_lshlrev_b32_e32 v32, 2, v2
	v_lshlrev_b32_e32 v34, 2, v4
	v_readlane_b32 s45, v253, 1
	v_readlane_b32 s46, v253, 2
	v_readlane_b32 s47, v253, 3
	v_readlane_b32 s48, v253, 4
	v_readlane_b32 s49, v253, 5
	v_readlane_b32 s17, v253, 43
	v_readlane_b32 s18, v253, 44
	v_readlane_b32 s19, v253, 45
	v_readlane_b32 s20, v253, 46
	v_readlane_b32 s21, v253, 47
	v_readlane_b32 s22, v253, 48
	v_readlane_b32 s23, v253, 49
	v_readlane_b32 s24, v253, 50
	v_readlane_b32 s25, v253, 51
	v_readlane_b32 s26, v253, 52
	v_readlane_b32 s27, v253, 53
	v_readlane_b32 s28, v253, 54
	v_readlane_b32 s29, v253, 55
	v_lshlrev_b32_e32 v29, 2, v16
	v_lshlrev_b32_e32 v31, 1, v16
	v_readfirstlane_b32 s0, v235
	s_lshr_b32 s0, s0, 6
	s_lshl_b32 s0, s0, 1
	s_lshl_b32 s2, s12, 3
	s_add_i32 s2, s2, s0
	s_mov_b32 s3, 3
.Lph_loop:
	s_cmpk_lt_u32 s2, 0x1000
	s_cselect_b32 s72, 1, 0
	s_add_i32 s73, s2, 0xfffff000
	s_lshr_b32 s0, s73, 11
	s_add_i32 s0, s0, 1
	s_cmp_lg_u32 s72, 0
	s_cselect_b32 s0, 0, s0
	s_mul_i32 s1, s52, 5
	s_add_i32 s0, s0, s1
	s_mul_i32 s0, s0, 0x3000
	v_readlane_b32 s20, v253, 4
	v_readlane_b32 s21, v253, 5
	s_nop 0
	s_add_u32 s20, s20, s0
	s_addc_u32 s21, s21, 0
	s_add_u32 s22, s20, 0x1000
	s_addc_u32 s23, s21, 0
	s_add_u32 s24, s20, 0x1e000
	s_addc_u32 s25, s21, 0
	s_add_u32 s26, s20, 0x1f000
	s_addc_u32 s27, s21, 0
	v_readlane_b32 s28, v253, 56
	v_readlane_b32 s29, v253, 57
	s_lshl_b32 s0, s52, 12
	s_add_u32 s28, s28, s0
	s_addc_u32 s29, s29, 0
	s_mul_i32 s0, s2, 0x880
	s_add_u32 s30, s56, s0
	s_addc_u32 s31, s57, 0
	s_add_u32 s44, s30, 0x880
	s_addc_u32 s45, s31, 0
	s_cmp_lg_u32 s52, 0
	s_cbranch_scc1 .Lph_src_out
	s_cmp_lg_u32 s72, 0
	s_cbranch_scc1 .Lph_src_prompt
	v_readlane_b32 s16, v253, 44
	v_readlane_b32 s17, v253, 45
	s_lshl_b32 s0, s73, 12
	s_add_u32 s16, s16, s0
	s_addc_u32 s17, s17, 0
	s_bfe_u32 s0, s2, 0x50006
	s_lshl_b32 s0, s0, 11
	v_readlane_b32 s46, v253, 6
	v_readlane_b32 s47, v253, 7
	s_and_b32 s1, s2, 63
	s_lshl_b32 s1, s1, 11
	v_readlane_b32 s48, v253, 58
	v_readlane_b32 s49, v253, 59
	s_add_u32 s46, s46, s0
	s_addc_u32 s47, s47, 0
	s_add_u32 s48, s48, s1
	s_addc_u32 s49, s49, 0
	s_add_u32 s50, s48, 0x800
	s_addc_u32 s51, s49, 0
	s_mov_b32 s74, 1
	s_branch .Lph_src_done
.Lph_src_prompt:
	v_readlane_b32 s16, v253, 42
	v_readlane_b32 s17, v253, 43
	s_lshl_b32 s0, s2, 12
	s_nop 0
	s_add_u32 s16, s16, s0
	s_addc_u32 s17, s17, 0
	s_mov_b32 s74, 0
	s_branch .Lph_src_done
.Lph_src_out:
	v_readlane_b32 s16, v254, 20
	v_readlane_b32 s17, v254, 21
	s_lshl_b32 s0, s2, 12
	s_nop 0
	s_add_u32 s16, s16, s0
	s_addc_u32 s17, s17, 0
	s_mov_b32 s74, 0
.Lph_src_done:
	s_add_u32 s18, s16, 0x1000
	s_addc_u32 s19, s17, 0
	s_nop 4
	global_load_dwordx4 v[112:115], v29, s[28:29]
	global_load_dwordx4 v[116:119], v29, s[20:21]
	global_load_dwordx4 v[120:123], v29, s[22:23]
	global_load_dwordx4 v[124:127], v29, s[24:25]
	global_load_dwordx4 v[128:131], v29, s[26:27]
	global_load_dwordx4 v[132:135], v29, s[28:29] offset:1024
	global_load_dwordx4 v[136:139], v29, s[20:21] offset:1024
	global_load_dwordx4 v[140:143], v29, s[22:23] offset:1024
	global_load_dwordx4 v[144:147], v29, s[24:25] offset:1024
	global_load_dwordx4 v[148:151], v29, s[26:27] offset:1024
	global_load_dwordx4 v[152:155], v29, s[28:29] offset:2048
	global_load_dwordx4 v[156:159], v29, s[20:21] offset:2048
	global_load_dwordx4 v[160:163], v29, s[22:23] offset:2048
	global_load_dwordx4 v[164:167], v29, s[24:25] offset:2048
	global_load_dwordx4 v[168:171], v29, s[26:27] offset:2048
	global_load_dwordx4 v[172:175], v29, s[28:29] offset:3072
	global_load_dwordx4 v[176:179], v29, s[20:21] offset:3072
	global_load_dwordx4 v[180:183], v29, s[22:23] offset:3072
	global_load_dwordx4 v[184:187], v29, s[24:25] offset:3072
	global_load_dwordx4 v[188:191], v29, s[26:27] offset:3072
	global_load_dwordx4 v[0:3], v29, s[16:17] nt
	global_load_dwordx4 v[4:7], v29, s[16:17] offset:1024 nt
	global_load_dwordx4 v[8:11], v29, s[16:17] offset:2048 nt
	global_load_dwordx4 v[12:15], v29, s[16:17] offset:3072 nt
	global_load_dwordx4 v[48:51], v29, s[18:19] nt
	global_load_dwordx4 v[52:55], v29, s[18:19] offset:1024 nt
	global_load_dwordx4 v[56:59], v29, s[18:19] offset:2048 nt
	global_load_dwordx4 v[60:63], v29, s[18:19] offset:3072 nt
	s_cmp_eq_u32 s74, 0
	s_cbranch_scc1 .Lph_nopos
	global_load_dwordx4 v[64:67], v29, s[46:47]
	global_load_dwordx4 v[68:71], v29, s[46:47] offset:1024
	global_load_dwordx4 v[72:75], v29, s[48:49]
	global_load_dwordx4 v[76:79], v29, s[48:49] offset:1024
	global_load_dwordx4 v[96:99], v29, s[50:51]
	global_load_dwordx4 v[100:103], v29, s[50:51] offset:1024
	s_waitcnt vmcnt(0)
	v_add_f32_e32 v0, v0, v64
	v_add_f32_e32 v48, v48, v64
	v_add_f32_e32 v1, v1, v65
	v_add_f32_e32 v49, v49, v65
	v_add_f32_e32 v2, v2, v66
	v_add_f32_e32 v50, v50, v66
	v_add_f32_e32 v3, v3, v67
	v_add_f32_e32 v51, v51, v67
	v_add_f32_e32 v4, v4, v68
	v_add_f32_e32 v52, v52, v68
	v_add_f32_e32 v5, v5, v69
	v_add_f32_e32 v53, v53, v69
	v_add_f32_e32 v6, v6, v70
	v_add_f32_e32 v54, v54, v70
	v_add_f32_e32 v7, v7, v71
	v_add_f32_e32 v55, v55, v71
	v_add_f32_e32 v8, v8, v72
	v_add_f32_e32 v56, v56, v96
	v_add_f32_e32 v9, v9, v73
	v_add_f32_e32 v57, v57, v97
	v_add_f32_e32 v10, v10, v74
	v_add_f32_e32 v58, v58, v98
	v_add_f32_e32 v11, v11, v75
	v_add_f32_e32 v59, v59, v99
	v_add_f32_e32 v12, v12, v76
	v_add_f32_e32 v60, v60, v100
	v_add_f32_e32 v13, v13, v77
	v_add_f32_e32 v61, v61, v101
	v_add_f32_e32 v14, v14, v78
	v_add_f32_e32 v62, v62, v102
	v_add_f32_e32 v15, v15, v79
	v_add_f32_e32 v63, v63, v103
.Lph_nopos:
	s_waitcnt vmcnt(0)
	v_mul_f32_e32 v33, v0, v0
	v_mul_f32_e32 v35, v48, v48
	v_fmac_f32_e32 v33, v1, v1
	v_fmac_f32_e32 v35, v49, v49
	v_fmac_f32_e32 v33, v2, v2
	v_fmac_f32_e32 v35, v50, v50
	v_fmac_f32_e32 v33, v3, v3
	v_fmac_f32_e32 v35, v51, v51
	v_fmac_f32_e32 v33, v4, v4
	v_fmac_f32_e32 v35, v52, v52
	v_fmac_f32_e32 v33, v5, v5
	v_fmac_f32_e32 v35, v53, v53
	v_fmac_f32_e32 v33, v6, v6
	v_fmac_f32_e32 v35, v54, v54
	v_fmac_f32_e32 v33, v7, v7
	v_fmac_f32_e32 v35, v55, v55
	v_fmac_f32_e32 v33, v8, v8
	v_fmac_f32_e32 v35, v56, v56
	v_fmac_f32_e32 v33, v9, v9
	v_fmac_f32_e32 v35, v57, v57
	v_fmac_f32_e32 v33, v10, v10
	v_fmac_f32_e32 v35, v58, v58
	v_fmac_f32_e32 v33, v11, v11
	v_fmac_f32_e32 v35, v59, v59
	v_fmac_f32_e32 v33, v12, v12
	v_fmac_f32_e32 v35, v60, v60
	v_fmac_f32_e32 v33, v13, v13
	v_fmac_f32_e32 v35, v61, v61
	v_fmac_f32_e32 v33, v14, v14
	v_fmac_f32_e32 v35, v62, v62
	v_fmac_f32_e32 v33, v15, v15
	v_fmac_f32_e32 v35, v63, v63
	ds_bpermute_b32 v36, v17, v33
	ds_bpermute_b32 v37, v17, v35
	s_waitcnt lgkmcnt(1)
	v_add_f32_e32 v33, v33, v36
	s_waitcnt lgkmcnt(0)
	v_add_f32_e32 v35, v35, v37
	ds_bpermute_b32 v36, v40, v33
	ds_bpermute_b32 v37, v40, v35
	s_waitcnt lgkmcnt(1)
	v_add_f32_e32 v33, v33, v36
	s_waitcnt lgkmcnt(0)
	v_add_f32_e32 v35, v35, v37
	ds_bpermute_b32 v36, v41, v33
	ds_bpermute_b32 v37, v41, v35
	s_waitcnt lgkmcnt(1)
	v_add_f32_e32 v33, v33, v36
	s_waitcnt lgkmcnt(0)
	v_add_f32_e32 v35, v35, v37
	ds_bpermute_b32 v36, v42, v33
	ds_bpermute_b32 v37, v42, v35
	s_waitcnt lgkmcnt(1)
	v_add_f32_e32 v33, v33, v36
	s_waitcnt lgkmcnt(0)
	v_add_f32_e32 v35, v35, v37
	ds_bpermute_b32 v36, v43, v33
	ds_bpermute_b32 v37, v43, v35
	s_waitcnt lgkmcnt(1)
	v_add_f32_e32 v33, v33, v36
	s_waitcnt lgkmcnt(0)
	v_add_f32_e32 v35, v35, v37
	ds_bpermute_b32 v36, v44, v33
	ds_bpermute_b32 v37, v44, v35
	s_waitcnt lgkmcnt(1)
	v_add_f32_e32 v33, v33, v36
	s_waitcnt lgkmcnt(0)
	v_add_f32_e32 v35, v35, v37
	v_fmamk_f32 v33, v33, 0x3a800000, v236
	v_fmamk_f32 v35, v35, 0x3a800000, v236
	v_rsq_f32_e32 v33, v33
	v_rsq_f32_e32 v35, v35
	s_nop 0
	v_mul_f32_e32 v0, v0, v33
	v_mul_f32_e32 v48, v48, v35
	v_mul_f32_e32 v1, v1, v33
	v_mul_f32_e32 v49, v49, v35
	v_mul_f32_e32 v2, v2, v33
	v_mul_f32_e32 v50, v50, v35
	v_mul_f32_e32 v3, v3, v33
	v_mul_f32_e32 v51, v51, v35
	v_mul_f32_e32 v4, v4, v33
	v_mul_f32_e32 v52, v52, v35
	v_mul_f32_e32 v5, v5, v33
	v_mul_f32_e32 v53, v53, v35
	v_mul_f32_e32 v6, v6, v33
	v_mul_f32_e32 v54, v54, v35
	v_mul_f32_e32 v7, v7, v33
	v_mul_f32_e32 v55, v55, v35
	v_mul_f32_e32 v8, v8, v33
	v_mul_f32_e32 v56, v56, v35
	v_mul_f32_e32 v9, v9, v33
	v_mul_f32_e32 v57, v57, v35
	v_mul_f32_e32 v10, v10, v33
	v_mul_f32_e32 v58, v58, v35
	v_mul_f32_e32 v11, v11, v33
	v_mul_f32_e32 v59, v59, v35
	v_mul_f32_e32 v12, v12, v33
	v_mul_f32_e32 v60, v60, v35
	v_mul_f32_e32 v13, v13, v33
	v_mul_f32_e32 v61, v61, v35
	v_mul_f32_e32 v14, v14, v33
	v_mul_f32_e32 v62, v62, v35
	v_mul_f32_e32 v15, v15, v33
	v_mul_f32_e32 v63, v63, v35
	v_add_f32_e32 v120, v120, v128
	v_add_f32_e32 v116, v116, v124
	v_add_f32_e32 v120, 1.0, v120
	v_add_f32_e32 v121, v121, v129
	v_add_f32_e32 v117, v117, v125
	v_add_f32_e32 v121, 1.0, v121
	v_add_f32_e32 v122, v122, v130
	v_add_f32_e32 v118, v118, v126
	v_add_f32_e32 v122, 1.0, v122
	v_add_f32_e32 v123, v123, v131
	v_add_f32_e32 v119, v119, v127
	v_add_f32_e32 v123, 1.0, v123
	v_mul_f32_e32 v0, v0, v112
	v_mul_f32_e32 v48, v48, v112
	v_fma_f32 v0, v0, v120, v116
	v_fma_f32 v48, v48, v120, v116
	v_mul_f32_e32 v1, v1, v113
	v_mul_f32_e32 v49, v49, v113
	v_fma_f32 v1, v1, v121, v117
	v_fma_f32 v49, v49, v121, v117
	v_mul_f32_e32 v2, v2, v114
	v_mul_f32_e32 v50, v50, v114
	v_fma_f32 v2, v2, v122, v118
	v_fma_f32 v50, v50, v122, v118
	v_mul_f32_e32 v3, v3, v115
	v_mul_f32_e32 v51, v51, v115
	v_fma_f32 v3, v3, v123, v119
	v_fma_f32 v51, v51, v123, v119
	v_cvt_pk_bf16_f32 v38, v0, v1
	v_cvt_pk_bf16_f32 v39, v2, v3
	v_cvt_pk_bf16_f32 v36, v48, v49
	v_cvt_pk_bf16_f32 v37, v50, v51
	global_store_dwordx2 v31, v[38:39], s[30:31]
	global_store_dwordx2 v31, v[36:37], s[44:45]
	v_add_f32_e32 v140, v140, v148
	v_add_f32_e32 v136, v136, v144
	v_add_f32_e32 v140, 1.0, v140
	v_add_f32_e32 v141, v141, v149
	v_add_f32_e32 v137, v137, v145
	v_add_f32_e32 v141, 1.0, v141
	v_add_f32_e32 v142, v142, v150
	v_add_f32_e32 v138, v138, v146
	v_add_f32_e32 v142, 1.0, v142
	v_add_f32_e32 v143, v143, v151
	v_add_f32_e32 v139, v139, v147
	v_add_f32_e32 v143, 1.0, v143
	v_mul_f32_e32 v4, v4, v132
	v_mul_f32_e32 v52, v52, v132
	v_fma_f32 v4, v4, v140, v136
	v_fma_f32 v52, v52, v140, v136
	v_mul_f32_e32 v5, v5, v133
	v_mul_f32_e32 v53, v53, v133
	v_fma_f32 v5, v5, v141, v137
	v_fma_f32 v53, v53, v141, v137
	v_mul_f32_e32 v6, v6, v134
	v_mul_f32_e32 v54, v54, v134
	v_fma_f32 v6, v6, v142, v138
	v_fma_f32 v54, v54, v142, v138
	v_mul_f32_e32 v7, v7, v135
	v_mul_f32_e32 v55, v55, v135
	v_fma_f32 v7, v7, v143, v139
	v_fma_f32 v55, v55, v143, v139
	v_cvt_pk_bf16_f32 v38, v4, v5
	v_cvt_pk_bf16_f32 v39, v6, v7
	v_cvt_pk_bf16_f32 v36, v52, v53
	v_cvt_pk_bf16_f32 v37, v54, v55
	global_store_dwordx2 v31, v[38:39], s[30:31] offset:512
	global_store_dwordx2 v31, v[36:37], s[44:45] offset:512
	v_add_f32_e32 v160, v160, v168
	v_add_f32_e32 v156, v156, v164
	v_add_f32_e32 v160, 1.0, v160
	v_add_f32_e32 v161, v161, v169
	v_add_f32_e32 v157, v157, v165
	v_add_f32_e32 v161, 1.0, v161
	v_add_f32_e32 v162, v162, v170
	v_add_f32_e32 v158, v158, v166
	v_add_f32_e32 v162, 1.0, v162
	v_add_f32_e32 v163, v163, v171
	v_add_f32_e32 v159, v159, v167
	v_add_f32_e32 v163, 1.0, v163
	v_mul_f32_e32 v8, v8, v152
	v_mul_f32_e32 v56, v56, v152
	v_fma_f32 v8, v8, v160, v156
	v_fma_f32 v56, v56, v160, v156
	v_mul_f32_e32 v9, v9, v153
	v_mul_f32_e32 v57, v57, v153
	v_fma_f32 v9, v9, v161, v157
	v_fma_f32 v57, v57, v161, v157
	v_mul_f32_e32 v10, v10, v154
	v_mul_f32_e32 v58, v58, v154
	v_fma_f32 v10, v10, v162, v158
	v_fma_f32 v58, v58, v162, v158
	v_mul_f32_e32 v11, v11, v155
	v_mul_f32_e32 v59, v59, v155
	v_fma_f32 v11, v11, v163, v159
	v_fma_f32 v59, v59, v163, v159
	v_cvt_pk_bf16_f32 v38, v8, v9
	v_cvt_pk_bf16_f32 v39, v10, v11
	v_cvt_pk_bf16_f32 v36, v56, v57
	v_cvt_pk_bf16_f32 v37, v58, v59
	global_store_dwordx2 v31, v[38:39], s[30:31] offset:1024
	global_store_dwordx2 v31, v[36:37], s[44:45] offset:1024
	v_add_f32_e32 v180, v180, v188
	v_add_f32_e32 v176, v176, v184
	v_add_f32_e32 v180, 1.0, v180
	v_add_f32_e32 v181, v181, v189
	v_add_f32_e32 v177, v177, v185
	v_add_f32_e32 v181, 1.0, v181
	v_add_f32_e32 v182, v182, v190
	v_add_f32_e32 v178, v178, v186
	v_add_f32_e32 v182, 1.0, v182
	v_add_f32_e32 v183, v183, v191
	v_add_f32_e32 v179, v179, v187
	v_add_f32_e32 v183, 1.0, v183
	v_mul_f32_e32 v12, v12, v172
	v_mul_f32_e32 v60, v60, v172
	v_fma_f32 v12, v12, v180, v176
	v_fma_f32 v60, v60, v180, v176
	v_mul_f32_e32 v13, v13, v173
	v_mul_f32_e32 v61, v61, v173
	v_fma_f32 v13, v13, v181, v177
	v_fma_f32 v61, v61, v181, v177
	v_mul_f32_e32 v14, v14, v174
	v_mul_f32_e32 v62, v62, v174
	v_fma_f32 v14, v14, v182, v178
	v_fma_f32 v62, v62, v182, v178
	v_mul_f32_e32 v15, v15, v175
	v_mul_f32_e32 v63, v63, v175
	v_fma_f32 v15, v15, v183, v179
	v_fma_f32 v63, v63, v183, v179
	v_cvt_pk_bf16_f32 v38, v12, v13
	v_cvt_pk_bf16_f32 v39, v14, v15
	v_cvt_pk_bf16_f32 v36, v60, v61
	v_cvt_pk_bf16_f32 v37, v62, v63
	global_store_dwordx2 v31, v[38:39], s[30:31] offset:1536
	global_store_dwordx2 v31, v[36:37], s[44:45] offset:1536
	s_add_i32 s2, s2, 0x1000
	s_add_i32 s3, s3, -1
	s_cmp_lg_u32 s3, 0
	s_cbranch_scc1 .Lph_loop
	v_readlane_b32 s44, v253, 0
	v_readlane_b32 s50, v253, 6
	v_readlane_b32 s51, v253, 7
